# NSA selected blocks: first block (always block 0) K/V tile loaded before the top-k selection code (guarded fallback to the original loads)
# speedup vs baseline: 1.0006x; 1.0006x over previous
; __device__ __forceinline__ void phase_nsa_attn(const Params& p, char* smem, volatile LAS unsigned* vb_) {
;     ...
;       lsum += __shfl_xor(lsum, 16);
;       lsum += __shfl_xor(lsum, 32);
;       const float sc = (lsum > 0.f) ? gt2 / lsum : 0.f;
; #pragma unroll
;       for (int dt = 0; dt < 4; ++dt)
; #pragma unroll
;         for (int r = 0; r < 4; ++r) yl[(dt * 4 + r) * 64] += o[dt][r] * sc;
;     }
;     {
;       const u16* Ks = KS + kvb * SEQL * 64;
;       const u16* Vs = VS + kvb * 64 * SEQL;
;       const int cur = s0 >> 6;
;       const int ncand = cur - 2;
;       u64 mk0[5], mk1[5];
; #pragma unroll
;       for (int i = 0; i < 5; ++i) { mk0[i] = 0; mk1[i] = 0; }
;       if (ncand <= 13) {
;         mk0[0] = (cur >= 63) ? ~0ull : ((1ull << (cur + 1)) - 1ull);
;       } else {
;         mk0[0] = 1ull;
;         if (cur - 1 < 64) mk0[0] |= 1ull << (cur - 1); else mk1[0] |= 1ull << (cur - 1 - 64);
;         if (cur < 64) mk0[0] |= 1ull << cur; else mk1[0] |= 1ull << (cur - 64);
.LBB0_106:
	s_or_b64 exec, exec, s[12:13]
	s_mov_b32 s98, 0x1000
	s_mov_b32 s99, 0
	global_load_dwordx4 v[88:91], v[146:147], off
	global_load_dwordx4 v[84:87], v[146:147], off offset:1024
	global_load_dwordx4 v[80:83], v[146:147], off offset:2048
	global_load_dwordx4 v[76:79], v[146:147], off offset:3072
	v_lshl_add_u64 v[214:215], v[146:147], 0, s[98:99]
	global_load_dwordx4 v[60:63], v[214:215], off
	global_load_dwordx4 v[52:55], v[214:215], off offset:1024
	global_load_dwordx4 v[44:47], v[214:215], off offset:2048
	global_load_dwordx4 v[210:213], v[214:215], off offset:3072
	global_load_dwordx4 v[72:75], v[148:149], off
	global_load_dwordx4 v[48:51], v[148:149], off offset:1024
	global_load_dwordx4 v[64:67], v[148:149], off offset:2048
	global_load_dwordx4 v[36:39], v[148:149], off offset:3072
	v_lshl_add_u64 v[214:215], v[148:149], 0, s[98:99]
	global_load_dwordx4 v[68:71], v[214:215], off
	global_load_dwordx4 v[40:43], v[214:215], off offset:1024
	global_load_dwordx4 v[56:59], v[214:215], off offset:2048
	global_load_dwordx4 v[32:35], v[214:215], off offset:3072
	ds_bpermute_b32 v0, v167, v99
	s_ashr_i32 s60, s10, 4
	s_mov_b32 s68, s96
	s_mov_b64 s[66:67], s[78:79]
	s_mov_b64 s[20:21], -1
	s_waitcnt lgkmcnt(0)
	v_add_f32_e32 v0, v99, v0
	ds_bpermute_b32 v2, v168, v0
	s_cmp_gt_i32 s60, 15
	s_waitcnt lgkmcnt(0)
	v_add_f32_e32 v0, v0, v2
	s_waitcnt vmcnt(16)
	v_div_scale_f32 v2, s[12:13], v0, v0, v118
	v_rcp_f32_e32 v3, v2
	v_cmp_lt_f32_e64 s[0:1], 0, v0
	s_waitcnt vmcnt(0)
	v_fma_f32 v28, -v2, v3, 1.0
	v_fmac_f32_e32 v3, v28, v3
	v_div_scale_f32 v28, vcc, v118, v0, v118
	v_mul_f32_e32 v29, v28, v3
	v_fma_f32 v30, -v2, v29, v28
	v_fmac_f32_e32 v29, v30, v3
	v_fma_f32 v2, -v2, v29, v28
	v_div_fmas_f32 v2, v2, v3, v29
	v_div_fixup_f32 v0, v2, v0, v118
	ds_read2st64_b32 v[2:3], v165 offset0:32 offset1:33
	v_cndmask_b32_e64 v0, 0, v0, s[0:1]
	s_waitcnt lgkmcnt(0)
	v_fma_f32 v2, v24, v0, v2
	v_fmac_f32_e32 v3, v25, v0
	ds_write2st64_b32 v165, v2, v3 offset0:32 offset1:33
	ds_read2st64_b32 v[2:3], v165 offset0:34 offset1:35
	s_waitcnt lgkmcnt(0)
	v_fma_f32 v2, v26, v0, v2
	v_fmac_f32_e32 v3, v27, v0
	ds_write2st64_b32 v165, v2, v3 offset0:34 offset1:35
	ds_read2st64_b32 v[2:3], v165 offset0:36 offset1:37
	s_waitcnt lgkmcnt(0)
	v_fma_f32 v2, v20, v0, v2
	v_fmac_f32_e32 v3, v21, v0
	ds_write2st64_b32 v165, v2, v3 offset0:36 offset1:37
	ds_read2st64_b32 v[2:3], v165 offset0:38 offset1:39
	s_waitcnt lgkmcnt(0)
	v_fma_f32 v2, v22, v0, v2
	v_fmac_f32_e32 v3, v23, v0
	ds_write2st64_b32 v165, v2, v3 offset0:38 offset1:39
	ds_read2st64_b32 v[2:3], v165 offset0:40 offset1:41
	s_waitcnt lgkmcnt(0)
	v_fma_f32 v2, v16, v0, v2
	v_fmac_f32_e32 v3, v17, v0
	ds_write2st64_b32 v165, v2, v3 offset0:40 offset1:41
	ds_read2st64_b32 v[2:3], v165 offset0:42 offset1:43
	s_waitcnt lgkmcnt(0)
	v_fma_f32 v2, v18, v0, v2
	v_fmac_f32_e32 v3, v19, v0
	ds_write2st64_b32 v165, v2, v3 offset0:42 offset1:43
	ds_read2st64_b32 v[2:3], v165 offset0:44 offset1:45
	s_waitcnt lgkmcnt(0)
	v_fma_f32 v2, v12, v0, v2
	v_fmac_f32_e32 v3, v13, v0
	ds_write2st64_b32 v165, v2, v3 offset0:44 offset1:45
	ds_read2st64_b32 v[2:3], v165 offset0:46 offset1:47
	s_waitcnt lgkmcnt(0)
	v_fma_f32 v2, v14, v0, v2
	v_fmac_f32_e32 v3, v15, v0
	ds_write2st64_b32 v165, v2, v3 offset0:46 offset1:47
	s_cbranch_scc0 .LBB0_165
	s_cmp_gt_u32 s60, 64
	s_mov_b64 s[10:11], -1
	s_cbranch_scc0 .LBB0_112
	s_add_i32 s0, s60, 0xffffffbf
	s_lshl_b64 s[0:1], 1, s0
	s_mov_b64 s[88:89], 1
	s_cbranch_execz .LBB0_113

; #define SB0 __builtin_amdgcn_sched_barrier(0)
; __device__ __forceinline__ void phase_nsa_attn(const Params& p, char* smem, volatile LAS unsigned* vb_) {
;     ...
;       u64 c0 = mk0[0] | mk0[1] | mk0[2] | mk0[3] | mk0[4];
;       u64 c1 = mk1[0] | mk1[1] | mk1[2] | mk1[3] | mk1[4];
;       const int ntot = __builtin_popcountll(c0) + __builtin_popcountll(c1);
;       const u64 my0 = mk0[0] | ((tq == 0) ? mk0[1] : (tq == 1) ? mk0[2] : (tq == 2) ? mk0[3] : mk0[4]);
;       const u64 my1 = mk1[0] | ((tq == 0) ? mk1[1] : (tq == 1) ? mk1[2] : (tq == 2) ? mk1[3] : mk1[4]);
;       int jn = 0;
;       auto advance = [&]() {
;         if (c0) { jn = __builtin_ctzll(c0); c0 &= c0 - 1ull; }
;         else if (c1) { jn = 64 + __builtin_ctzll(c1); c1 &= c1 - 1ull; }
;       };
;       float m = -1e30f, lsum = 0.f;
;       f32x4 o[4];
; #pragma unroll
;       for (int dt = 0; dt < 4; ++dt) o[dt] = (f32x4){0.f, 0.f, 0.f, 0.f};
;       advance();
;       SB0;
;       k_load64(kA, Ks + (size_t)jn * 4096, lane);
;       SB0;
;       v_load64(vA, Vs + (size_t)jn * 4096, lane);
;       SB0;
;       for (int i = 0; i < ntot; ++i) {
.LBB0_172:
	s_bcnt1_i32_b64 s37, s[82:83]
	s_bcnt1_i32_b64 s52, s[52:53]
	s_add_i32 s52, s52, s37
	s_mov_b32 s37, s59
	s_lshl_b64 s[62:63], s[36:37], 13
	s_cmp_eq_u32 s36, 0
	s_cbranch_scc0 .Lsel_reload
	s_waitcnt vmcnt(8)
	v_mov_b64_e32 v[28:29], v[210:211]
	v_mov_b64_e32 v[30:31], v[212:213]
	s_branch .Lsel_loaded
.Lsel_reload:
	v_lshl_add_u64 v[2:3], v[146:147], 0, s[62:63]
	global_load_dwordx4 v[88:91], v[2:3], off
	global_load_dwordx4 v[84:87], v[2:3], off offset:1024
	global_load_dwordx4 v[80:83], v[2:3], off offset:2048
	global_load_dwordx4 v[76:79], v[2:3], off offset:3072
	v_add_co_u32_e32 v2, vcc, s33, v2
	s_nop 1
	v_addc_co_u32_e32 v3, vcc, 0, v3, vcc
	global_load_dwordx4 v[60:63], v[2:3], off
	global_load_dwordx4 v[52:55], v[2:3], off offset:1024
	global_load_dwordx4 v[44:47], v[2:3], off offset:2048
	global_load_dwordx4 v[28:31], v[2:3], off offset:3072
	v_lshl_add_u64 v[2:3], v[148:149], 0, s[62:63]
	global_load_dwordx4 v[72:75], v[2:3], off
	global_load_dwordx4 v[48:51], v[2:3], off offset:1024
	global_load_dwordx4 v[64:67], v[2:3], off offset:2048
	global_load_dwordx4 v[36:39], v[2:3], off offset:3072
	v_add_co_u32_e32 v2, vcc, 0x1000, v2
	s_nop 1
	v_addc_co_u32_e32 v3, vcc, 0, v3, vcc
	global_load_dwordx4 v[68:71], v[2:3], off
	global_load_dwordx4 v[40:43], v[2:3], off offset:1024
	global_load_dwordx4 v[56:59], v[2:3], off offset:2048
	global_load_dwordx4 v[32:35], v[2:3], off offset:3072
.Lsel_loaded:
	s_cmp_eq_u32 s52, 0
	s_cbranch_scc1 .LBB0_88
	v_mov_b32_e32 v0, s79
	v_mov_b32_e32 v2, s97
	v_cndmask_b32_e64 v0, v0, v2, s[50:51]
	v_mov_b32_e32 v2, s78
	v_mov_b32_e32 v3, s96
	v_cndmask_b32_e64 v2, v2, v3, s[50:51]
	v_mov_b32_e32 v3, s38
	v_cndmask_b32_e64 v2, v2, v3, s[48:49]
	v_mov_b32_e32 v3, s39
	v_cndmask_b32_e64 v0, v0, v3, s[48:49]
	v_mov_b32_e32 v3, s13
	v_cndmask_b32_e64 v0, v0, v3, s[46:47]
	v_mov_b32_e32 v3, s12
	v_cndmask_b32_e64 v2, v2, v3, s[46:47]
	v_mov_b32_e32 v3, s85
	v_mov_b32_e32 v12, s41
	v_cndmask_b32_e64 v3, v3, v12, s[50:51]
	v_mov_b32_e32 v12, s84
	v_mov_b32_e32 v13, s40
	v_cndmask_b32_e64 v12, v12, v13, s[50:51]
	v_mov_b32_e32 v13, s22
	v_cndmask_b32_e64 v12, v12, v13, s[48:49]
	v_mov_b32_e32 v13, s23
	v_cndmask_b32_e64 v3, v3, v13, s[48:49]
	v_mov_b32_e32 v13, s91
	v_cndmask_b32_e64 v3, v3, v13, s[46:47]
	v_mov_b32_e32 v13, s90
	v_cndmask_b32_e64 v12, v12, v13, s[46:47]
	v_or_b32_e32 v92, s88, v2
	v_or_b32_e32 v95, s1, v3
	v_mov_b32_e32 v2, v1
	v_mov_b32_e32 v3, v1
	v_or_b32_e32 v93, s89, v0
	v_or_b32_e32 v94, s0, v12
	v_mov_b32_e32 v0, v1
	v_mov_b64_e32 v[14:15], v[2:3]
	v_mov_b64_e32 v[18:19], v[2:3]
	v_mov_b64_e32 v[22:23], v[2:3]
	v_mov_b64_e32 v[26:27], v[2:3]
	s_mov_b32 s12, 0
	v_mov_b32_e32 v97, 0xf149f2ca
	v_mov_b32_e32 v96, 0
	v_mov_b64_e32 v[12:13], v[0:1]
	v_mov_b64_e32 v[16:17], v[0:1]
	v_mov_b64_e32 v[20:21], v[0:1]
	v_mov_b64_e32 v[24:25], v[0:1]
	s_mov_b64 s[78:79], s[66:67]
	s_mov_b32 s96, s68
	s_movk_i32 s97, 0x600
	s_add_i32 s12, s12, 1
	s_cmp_ge_u32 s12, s52
	s_cbranch_scc0 .LBB0_175
